# grid barrier: non-leader workgroups poll the cross-XCD release generation directly instead of the per-XCD forwarded generation (one poll hop less per barrier, 20 barriers)
# speedup vs baseline: 1.0084x; 1.0015x over previous
; __device__ __forceinline__ unsigned xb_ld(unsigned* p)              { return __hip_atomic_load(p, __ATOMIC_RELAXED, __HIP_MEMORY_SCOPE_AGENT); }
; __device__ __forceinline__ unsigned xb_add(unsigned* p, unsigned v) { return __hip_atomic_fetch_add(p, v, __ATOMIC_RELAXED, __HIP_MEMORY_SCOPE_AGENT); }
; #define XB_SPIN(cond, bar) do { unsigned _sp = 0; while (cond) { __builtin_amdgcn_s_sleep(1); \
;     if ((++_sp & 255u) == 0u) { if (xb_ld(&(bar)[XB_TMO])) break; if (_sp > XB_SPIN_CAP) { atomicAdd(&(bar)[XB_TMO], 1u); break; } } } } while (0)
; __device__ __forceinline__ void xcd_barrier(const XcdBarrier& b) {
;     ...
;         const unsigned old = xb_add(&bar[XB_XSUB(b.x)], 1u);
;         const unsigned gen = old / nloc;
;         if (old + 1u == (gen + 1u) * nloc) {
;             __builtin_amdgcn_fence(__ATOMIC_RELEASE, "agent");
;             asm volatile("s_waitcnt vmcnt(0)" ::: "memory");
;             const unsigned og = xb_add(&bar[XB_TOP], 1u);
;             const unsigned tg = og / nx;
;             if (og + 1u == (tg + 1u) * nx) xb_add(&bar[XB_TOPGEN], 1u);
;             else XB_SPIN(xb_ld(&bar[XB_TOPGEN]) == tg, bar);
;             __builtin_amdgcn_fence(__ATOMIC_ACQUIRE, "agent");
;             xb_add(&bar[XB_XGEN(b.x)], 1u);
;             asm volatile("s_waitcnt vmcnt(0)" ::: "memory");
;         } else {
;             XB_SPIN(xb_ld(&bar[XB_XGEN(b.x)]) == gen, bar);
.LBB0_547:
	s_or_b64 exec, exec, s[10:11]
	v_cvt_f32_u32_e32 v5, v3
	s_waitcnt vmcnt(0)
	v_readfirstlane_b32 s8, v4
	s_add_u32 s6, s6, 0x2400
	s_addc_u32 s7, s7, 0
	v_rcp_iflag_f32_e32 v5, v5
	v_add_u32_e32 v6, s8, v2
	v_mul_f32_e32 v4, 0x4f7ffffe, v5
	v_cvt_u32_f32_e32 v4, v4
	v_sub_u32_e32 v5, 0, v3
	v_mul_lo_u32 v2, v5, v4
	v_mul_hi_u32 v2, v4, v2
	v_add_u32_e32 v2, v4, v2
	v_mul_hi_u32 v2, v6, v2
	v_mul_lo_u32 v4, v2, v3
	v_sub_u32_e32 v4, v6, v4
	v_add_u32_e32 v5, 1, v2
	v_cmp_ge_u32_e32 vcc, v4, v3
	s_nop 1
	v_cndmask_b32_e32 v2, v2, v5, vcc
	v_sub_u32_e32 v5, v4, v3
	v_cndmask_b32_e32 v4, v4, v5, vcc
	v_add_u32_e32 v5, 1, v2
	v_cmp_ge_u32_e32 vcc, v4, v3
	v_add_u32_e32 v4, 1, v6
	s_nop 0
	v_cndmask_b32_e32 v2, v2, v5, vcc
	v_mul_lo_u32 v5, v3, v2
	v_add_u32_e32 v3, v5, v3
	v_cmp_ne_u32_e32 vcc, v4, v3
	s_and_saveexec_b64 s[8:9], vcc
	s_xor_b64 s[8:9], exec, s[8:9]
	s_cbranch_execz .LBB0_561
	s_waitcnt lgkmcnt(0)
	v_mov_b32_e32 v4, 0x7500
	global_load_dword v0, v4, s[4:5] sc1
	s_waitcnt vmcnt(0)
	v_cmp_eq_u32_e32 vcc, v0, v2
	s_and_saveexec_b64 s[10:11], vcc
	s_cbranch_execz .LBB0_560
	s_mov_b32 s21, 1
	s_mov_b64 s[12:13], 0
	s_branch .LBB0_551

; __device__ __forceinline__ unsigned xb_ld(unsigned* p)              { return __hip_atomic_load(p, __ATOMIC_RELAXED, __HIP_MEMORY_SCOPE_AGENT); }
; #define XB_SPIN(cond, bar) do { unsigned _sp = 0; while (cond) { __builtin_amdgcn_s_sleep(1); \
;     if ((++_sp & 255u) == 0u) { if (xb_ld(&(bar)[XB_TMO])) break; if (_sp > XB_SPIN_CAP) { atomicAdd(&(bar)[XB_TMO], 1u); break; } } } } while (0)
; __device__ __forceinline__ void xcd_barrier(const XcdBarrier& b) {
;     ...
;             XB_SPIN(xb_ld(&bar[XB_XGEN(b.x)]) == gen, bar);
.LBB0_553:
	global_load_dword v0, v4, s[4:5] sc1
	s_add_i32 s21, s21, 1
	s_mov_b64 s[18:19], -1
	s_waitcnt vmcnt(0)
	v_cmp_ne_u32_e32 vcc, v0, v2
	s_orn2_b64 s[16:17], vcc, exec
	s_branch .LBB0_550
